# gate/up GEMM K loop: loop-control and next-iteration address SALU moved from the segment head into the last compute segment's MFMA shadow
# baseline (speedup 1.0000x reference)
.LBB0_811:
	s_ashr_i32 s17, s16, 31
	s_lshl_b64 s[18:19], s[16:17], 19
	s_add_u32 s18, s28, s18
	s_addc_u32 s19, s29, s19
	s_and_b64 s[26:27], s[34:35], exec
	s_cselect_b32 s17, s19, s37
	s_cselect_b32 s50, s18, s36
	s_ashr_i32 s15, s14, 31
	s_lshl_b64 s[26:27], s[14:15], 19
	s_add_u32 s26, s0, s26
	s_addc_u32 s27, s6, s27
	s_and_b64 s[40:41], s[34:35], exec
	s_cselect_b32 s15, s27, s39
	s_cselect_b32 s51, s26, s38
	s_add_u32 s36, s36, 0x40080
	s_addc_u32 s37, s37, 0
	s_add_u32 s52, s38, 0x100
	v_mov_b32_e32 v2, 0
	s_addc_u32 s53, s39, 0
	s_mov_b32 s54, -2
	v_mov_b32_e32 v3, v2
	v_pk_mov_b32 v[4:5], v[2:3], v[2:3]
	v_pk_mov_b32 v[6:7], v[2:3], v[2:3]
	v_pk_mov_b32 v[8:9], v[2:3], v[2:3]
	v_pk_mov_b32 v[10:11], v[2:3], v[2:3]
	v_pk_mov_b32 v[12:13], v[2:3], v[2:3]
	v_pk_mov_b32 v[14:15], v[2:3], v[2:3]
	v_pk_mov_b32 v[16:17], v[2:3], v[2:3]
	v_pk_mov_b32 v[18:19], v[2:3], v[2:3]
	v_pk_mov_b32 v[20:21], v[2:3], v[2:3]
	v_pk_mov_b32 v[22:23], v[2:3], v[2:3]
	v_pk_mov_b32 v[24:25], v[2:3], v[2:3]
	v_pk_mov_b32 v[26:27], v[2:3], v[2:3]
	v_pk_mov_b32 v[28:29], v[2:3], v[2:3]
	v_pk_mov_b32 v[30:31], v[2:3], v[2:3]
	v_pk_mov_b32 v[32:33], v[2:3], v[2:3]
	v_pk_mov_b32 v[34:35], v[2:3], v[2:3]
	v_pk_mov_b32 v[36:37], v[2:3], v[2:3]
	v_pk_mov_b32 v[38:39], v[2:3], v[2:3]
	v_pk_mov_b32 v[40:41], v[2:3], v[2:3]
	v_pk_mov_b32 v[42:43], v[2:3], v[2:3]
	v_pk_mov_b32 v[44:45], v[2:3], v[2:3]
	v_pk_mov_b32 v[46:47], v[2:3], v[2:3]
	v_pk_mov_b32 v[48:49], v[2:3], v[2:3]
	v_pk_mov_b32 v[50:51], v[2:3], v[2:3]
	v_pk_mov_b32 v[52:53], v[2:3], v[2:3]
	v_pk_mov_b32 v[54:55], v[2:3], v[2:3]
	v_pk_mov_b32 v[56:57], v[2:3], v[2:3]
	v_pk_mov_b32 v[58:59], v[2:3], v[2:3]
	v_pk_mov_b32 v[60:61], v[2:3], v[2:3]
	v_pk_mov_b32 v[62:63], v[2:3], v[2:3]
	v_pk_mov_b32 v[64:65], v[2:3], v[2:3]
	v_pk_mov_b32 v[66:67], v[2:3], v[2:3]
	v_pk_mov_b32 v[68:69], v[2:3], v[2:3]
	v_pk_mov_b32 v[70:71], v[2:3], v[2:3]
	v_pk_mov_b32 v[72:73], v[2:3], v[2:3]
	v_pk_mov_b32 v[74:75], v[2:3], v[2:3]
	v_pk_mov_b32 v[76:77], v[2:3], v[2:3]
	v_pk_mov_b32 v[78:79], v[2:3], v[2:3]
	v_pk_mov_b32 v[80:81], v[2:3], v[2:3]
	v_pk_mov_b32 v[82:83], v[2:3], v[2:3]
	v_pk_mov_b32 v[84:85], v[2:3], v[2:3]
	v_pk_mov_b32 v[86:87], v[2:3], v[2:3]
	v_pk_mov_b32 v[88:89], v[2:3], v[2:3]
	v_pk_mov_b32 v[90:91], v[2:3], v[2:3]
	v_pk_mov_b32 v[92:93], v[2:3], v[2:3]
	v_pk_mov_b32 v[94:95], v[2:3], v[2:3]
	v_pk_mov_b32 v[96:97], v[2:3], v[2:3]
	v_pk_mov_b32 v[98:99], v[2:3], v[2:3]
	v_pk_mov_b32 v[100:101], v[2:3], v[2:3]
	v_pk_mov_b32 v[102:103], v[2:3], v[2:3]
	v_pk_mov_b32 v[104:105], v[2:3], v[2:3]
	v_pk_mov_b32 v[106:107], v[2:3], v[2:3]
	v_pk_mov_b32 v[108:109], v[2:3], v[2:3]
	v_pk_mov_b32 v[110:111], v[2:3], v[2:3]
	v_pk_mov_b32 v[112:113], v[2:3], v[2:3]
	v_pk_mov_b32 v[114:115], v[2:3], v[2:3]
	v_pk_mov_b32 v[116:117], v[2:3], v[2:3]
	v_pk_mov_b32 v[118:119], v[2:3], v[2:3]
	v_pk_mov_b32 v[120:121], v[2:3], v[2:3]
	v_pk_mov_b32 v[122:123], v[2:3], v[2:3]
	v_pk_mov_b32 v[124:125], v[2:3], v[2:3]
	v_pk_mov_b32 v[126:127], v[2:3], v[2:3]
	v_pk_mov_b32 v[128:129], v[2:3], v[2:3]
	s_add_u32 s38, s36, 0xfffc0080
	s_addc_u32 s39, s37, -1
	s_add_i32 s55, 0, 0x10000
	s_cmp_eq_u32 s54, 12
	s_cselect_b32 s41, s17, s39
	s_cselect_b32 s40, s50, s38
	v_add_u32_e32 v149, s55, v145
	s_cselect_b32 s39, s15, s53
	s_cselect_b32 s38, s51, s52
	s_add_i32 s58, 0, 0x14000
.LBB0_812:
	ds_read_b128 v[140:143], v149
	ds_read_b128 v[150:153], v149 offset:1024
	ds_read_b128 v[164:167], v149 offset:2048
	ds_read_b128 v[168:171], v149 offset:3072
	v_add_u32_e32 v149, s58, v145
	ds_read_b128 v[176:179], v149
	ds_read_b128 v[180:183], v149 offset:1024
	ds_read_b128 v[184:187], v149 offset:2048
	ds_read_b128 v[212:215], v149 offset:3072
	v_lshl_add_u64 v[154:155], s[36:37], 0, v[136:137]
	s_add_i32 m0, s42, 0xc000
	ds_read_b128 v[216:219], v148
	ds_read_b128 v[220:223], v148 offset:1024
	ds_read_b128 v[224:227], v148 offset:2048
	ds_read_b128 v[228:231], v148 offset:3072
	ds_read_b128 v[232:235], v148 offset:4096
	ds_read_b128 v[236:239], v148 offset:5120
	ds_read_b128 v[240:243], v148 offset:6144
	ds_read_b128 v[244:247], v148 offset:7168
	global_load_lds_dwordx4 v[154:155], off
	v_lshl_add_u64 v[154:155], s[36:37], 0, v[138:139]
	s_add_i32 m0, s42, 0xe000
	s_nop 0
	global_load_lds_dwordx4 v[154:155], off
	s_waitcnt vmcnt(8)
	s_waitcnt lgkmcnt(0)
	s_barrier
	s_setprio 1
	s_waitcnt lgkmcnt(0)
	v_mfma_f32_16x16x32_bf16 v[126:129], v[140:143], v[216:219], v[126:129]
	v_mfma_f32_16x16x32_bf16 v[118:121], v[164:167], v[216:219], v[118:121]
	v_mfma_f32_16x16x32_bf16 v[110:113], v[140:143], v[224:227], v[110:113]
	v_mfma_f32_16x16x32_bf16 v[102:105], v[164:167], v[224:227], v[102:105]
	v_mfma_f32_16x16x32_bf16 v[94:97], v[140:143], v[232:235], v[94:97]
	v_mfma_f32_16x16x32_bf16 v[86:89], v[164:167], v[232:235], v[86:89]
	v_mfma_f32_16x16x32_bf16 v[78:81], v[140:143], v[240:243], v[78:81]
	v_mfma_f32_16x16x32_bf16 v[70:73], v[164:167], v[240:243], v[70:73]
	v_mfma_f32_16x16x32_bf16 v[126:129], v[150:153], v[220:223], v[126:129]
	v_mfma_f32_16x16x32_bf16 v[118:121], v[168:171], v[220:223], v[118:121]
	v_mfma_f32_16x16x32_bf16 v[110:113], v[150:153], v[228:231], v[110:113]
	v_mfma_f32_16x16x32_bf16 v[102:105], v[168:171], v[228:231], v[102:105]
	v_mfma_f32_16x16x32_bf16 v[94:97], v[150:153], v[236:239], v[94:97]
	v_mfma_f32_16x16x32_bf16 v[86:89], v[168:171], v[236:239], v[86:89]
	v_mfma_f32_16x16x32_bf16 v[78:81], v[150:153], v[244:247], v[78:81]
	v_mfma_f32_16x16x32_bf16 v[70:73], v[168:171], v[244:247], v[70:73]
	s_setprio 0
	s_setprio 1
	v_mfma_f32_16x16x32_bf16 v[122:125], v[176:179], v[216:219], v[122:125]
	v_mfma_f32_16x16x32_bf16 v[114:117], v[184:187], v[216:219], v[114:117]
	v_mfma_f32_16x16x32_bf16 v[106:109], v[176:179], v[224:227], v[106:109]
	v_mfma_f32_16x16x32_bf16 v[98:101], v[184:187], v[224:227], v[98:101]
	v_mfma_f32_16x16x32_bf16 v[90:93], v[176:179], v[232:235], v[90:93]
	v_mfma_f32_16x16x32_bf16 v[82:85], v[184:187], v[232:235], v[82:85]
	v_mfma_f32_16x16x32_bf16 v[74:77], v[176:179], v[240:243], v[74:77]
	v_mfma_f32_16x16x32_bf16 v[66:69], v[184:187], v[240:243], v[66:69]
	v_mfma_f32_16x16x32_bf16 v[122:125], v[180:183], v[220:223], v[122:125]
	v_mfma_f32_16x16x32_bf16 v[114:117], v[212:215], v[220:223], v[114:117]
	v_mfma_f32_16x16x32_bf16 v[106:109], v[180:183], v[228:231], v[106:109]
	v_mfma_f32_16x16x32_bf16 v[98:101], v[212:215], v[228:231], v[98:101]
	v_mfma_f32_16x16x32_bf16 v[90:93], v[180:183], v[236:239], v[90:93]
	v_mfma_f32_16x16x32_bf16 v[82:85], v[212:215], v[236:239], v[82:85]
	v_mfma_f32_16x16x32_bf16 v[74:77], v[180:183], v[244:247], v[74:77]
	v_mfma_f32_16x16x32_bf16 v[66:69], v[212:215], v[244:247], v[66:69]
	s_setprio 0
	s_barrier
	s_add_i32 s55, s55, s7
	v_lshl_add_u64 v[154:155], s[38:39], 0, v[0:1]
	s_mov_b32 m0, s55
	ds_read_b128 v[216:219], v148 offset:16384
	ds_read_b128 v[220:223], v148 offset:17408
	ds_read_b128 v[224:227], v148 offset:18432
	ds_read_b128 v[228:231], v148 offset:19456
	ds_read_b128 v[232:235], v148 offset:20480
	ds_read_b128 v[236:239], v148 offset:21504
	ds_read_b128 v[240:243], v148 offset:22528
	ds_read_b128 v[244:247], v148 offset:23552
	global_load_lds_dwordx4 v[154:155], off
	s_add_i32 m0, s55, 0x2000
	s_add_u32 s56, s38, 0x40000
	v_lshl_add_u64 v[172:173], s[38:39], 0, v[134:135]
	s_addc_u32 s57, s39, 0
	s_add_i32 s55, s58, s7
	global_load_lds_dwordx4 v[172:173], off
	v_lshl_add_u64 v[248:249], s[56:57], 0, v[0:1]
	s_mov_b32 m0, s55
	v_lshl_add_u64 v[250:251], s[40:41], 0, v[132:133]
	global_load_lds_dwordx4 v[248:249], off
	v_lshl_add_u64 v[248:249], s[56:57], 0, v[134:135]
	s_add_i32 m0, s55, 0x2000
	s_nop 0
	global_load_lds_dwordx4 v[248:249], off
	v_lshl_add_u64 v[248:249], s[40:41], 0, v[130:131]
	s_mov_b32 m0, s42
	s_nop 0
	global_load_lds_dwordx4 v[248:249], off
	s_mov_b32 m0, s43
	s_nop 0
	global_load_lds_dwordx4 v[250:251], off
	s_waitcnt vmcnt(8)
	s_waitcnt lgkmcnt(0)
	s_barrier
	s_setprio 1
	s_waitcnt lgkmcnt(0)
	v_mfma_f32_16x16x32_bf16 v[62:65], v[140:143], v[216:219], v[62:65]
	v_mfma_f32_16x16x32_bf16 v[54:57], v[164:167], v[216:219], v[54:57]
	v_mfma_f32_16x16x32_bf16 v[46:49], v[140:143], v[224:227], v[46:49]
	v_mfma_f32_16x16x32_bf16 v[38:41], v[164:167], v[224:227], v[38:41]
	v_mfma_f32_16x16x32_bf16 v[30:33], v[140:143], v[232:235], v[30:33]
	v_mfma_f32_16x16x32_bf16 v[22:25], v[164:167], v[232:235], v[22:25]
	v_mfma_f32_16x16x32_bf16 v[14:17], v[140:143], v[240:243], v[14:17]
	v_mfma_f32_16x16x32_bf16 v[6:9], v[164:167], v[240:243], v[6:9]
	v_mfma_f32_16x16x32_bf16 v[62:65], v[150:153], v[220:223], v[62:65]
	v_mfma_f32_16x16x32_bf16 v[54:57], v[168:171], v[220:223], v[54:57]
	v_mfma_f32_16x16x32_bf16 v[46:49], v[150:153], v[228:231], v[46:49]
	v_mfma_f32_16x16x32_bf16 v[38:41], v[168:171], v[228:231], v[38:41]
	v_mfma_f32_16x16x32_bf16 v[30:33], v[150:153], v[236:239], v[30:33]
	v_mfma_f32_16x16x32_bf16 v[22:25], v[168:171], v[236:239], v[22:25]
	v_mfma_f32_16x16x32_bf16 v[14:17], v[150:153], v[244:247], v[14:17]
	v_mfma_f32_16x16x32_bf16 v[6:9], v[168:171], v[244:247], v[6:9]
	s_setprio 0
	s_setprio 1
	v_mfma_f32_16x16x32_bf16 v[58:61], v[176:179], v[216:219], v[58:61]
	v_mfma_f32_16x16x32_bf16 v[50:53], v[184:187], v[216:219], v[50:53]
	v_mfma_f32_16x16x32_bf16 v[42:45], v[176:179], v[224:227], v[42:45]
	v_mfma_f32_16x16x32_bf16 v[34:37], v[184:187], v[224:227], v[34:37]
	v_mfma_f32_16x16x32_bf16 v[26:29], v[176:179], v[232:235], v[26:29]
	v_mfma_f32_16x16x32_bf16 v[18:21], v[184:187], v[232:235], v[18:21]
	v_mfma_f32_16x16x32_bf16 v[10:13], v[176:179], v[240:243], v[10:13]
	v_mfma_f32_16x16x32_bf16 v[2:5], v[184:187], v[240:243], v[2:5]
	v_mfma_f32_16x16x32_bf16 v[58:61], v[180:183], v[220:223], v[58:61]
	v_mfma_f32_16x16x32_bf16 v[50:53], v[212:215], v[220:223], v[50:53]
	v_mfma_f32_16x16x32_bf16 v[42:45], v[180:183], v[228:231], v[42:45]
	v_mfma_f32_16x16x32_bf16 v[34:37], v[212:215], v[228:231], v[34:37]
	v_mfma_f32_16x16x32_bf16 v[26:29], v[180:183], v[236:239], v[26:29]
	v_mfma_f32_16x16x32_bf16 v[18:21], v[212:215], v[236:239], v[18:21]
	v_mfma_f32_16x16x32_bf16 v[10:13], v[180:183], v[244:247], v[10:13]
	v_mfma_f32_16x16x32_bf16 v[2:5], v[212:215], v[244:247], v[2:5]
	s_setprio 0
	s_barrier
	s_add_i32 s55, 0, 0x18000
	v_add_u32_e32 v149, s55, v145
	s_add_i32 s56, 0, 0x1c000
	ds_read_b128 v[140:143], v149
	ds_read_b128 v[150:153], v149 offset:1024
	ds_read_b128 v[164:167], v149 offset:2048
	ds_read_b128 v[168:171], v149 offset:3072
	v_add_u32_e32 v149, s56, v145
	ds_read_b128 v[176:179], v149
	ds_read_b128 v[180:183], v149 offset:1024
	ds_read_b128 v[184:187], v149 offset:2048
	ds_read_b128 v[212:215], v149 offset:3072
	s_add_u32 s40, s40, 0x40000
	s_addc_u32 s41, s41, 0
	s_mov_b32 m0, s44
	v_lshl_add_u64 v[198:199], s[40:41], 0, v[130:131]
	ds_read_b128 v[216:219], v148 offset:32768
	ds_read_b128 v[220:223], v148 offset:33792
	ds_read_b128 v[224:227], v148 offset:34816
	ds_read_b128 v[228:231], v148 offset:35840
	ds_read_b128 v[232:235], v148 offset:36864
	ds_read_b128 v[236:239], v148 offset:37888
	ds_read_b128 v[240:243], v148 offset:38912
	ds_read_b128 v[244:247], v148 offset:39936
	global_load_lds_dwordx4 v[198:199], off
	v_lshl_add_u64 v[198:199], s[40:41], 0, v[132:133]
	s_mov_b32 m0, s45
	s_nop 0
	global_load_lds_dwordx4 v[198:199], off
	s_waitcnt vmcnt(8)
	s_waitcnt lgkmcnt(0)
	s_barrier
	s_setprio 1
	s_waitcnt lgkmcnt(0)
	v_mfma_f32_16x16x32_bf16 v[126:129], v[140:143], v[216:219], v[126:129]
	v_mfma_f32_16x16x32_bf16 v[118:121], v[164:167], v[216:219], v[118:121]
	v_mfma_f32_16x16x32_bf16 v[110:113], v[140:143], v[224:227], v[110:113]
	v_mfma_f32_16x16x32_bf16 v[102:105], v[164:167], v[224:227], v[102:105]
	v_mfma_f32_16x16x32_bf16 v[94:97], v[140:143], v[232:235], v[94:97]
	v_mfma_f32_16x16x32_bf16 v[86:89], v[164:167], v[232:235], v[86:89]
	v_mfma_f32_16x16x32_bf16 v[78:81], v[140:143], v[240:243], v[78:81]
	v_mfma_f32_16x16x32_bf16 v[70:73], v[164:167], v[240:243], v[70:73]
	v_mfma_f32_16x16x32_bf16 v[126:129], v[150:153], v[220:223], v[126:129]
	v_mfma_f32_16x16x32_bf16 v[118:121], v[168:171], v[220:223], v[118:121]
	v_mfma_f32_16x16x32_bf16 v[110:113], v[150:153], v[228:231], v[110:113]
	v_mfma_f32_16x16x32_bf16 v[102:105], v[168:171], v[228:231], v[102:105]
	v_mfma_f32_16x16x32_bf16 v[94:97], v[150:153], v[236:239], v[94:97]
	v_mfma_f32_16x16x32_bf16 v[86:89], v[168:171], v[236:239], v[86:89]
	v_mfma_f32_16x16x32_bf16 v[78:81], v[150:153], v[244:247], v[78:81]
	v_mfma_f32_16x16x32_bf16 v[70:73], v[168:171], v[244:247], v[70:73]
	s_setprio 0
	s_setprio 1
	v_mfma_f32_16x16x32_bf16 v[122:125], v[176:179], v[216:219], v[122:125]
	v_mfma_f32_16x16x32_bf16 v[114:117], v[184:187], v[216:219], v[114:117]
	v_mfma_f32_16x16x32_bf16 v[106:109], v[176:179], v[224:227], v[106:109]
	v_mfma_f32_16x16x32_bf16 v[98:101], v[184:187], v[224:227], v[98:101]
	v_mfma_f32_16x16x32_bf16 v[90:93], v[176:179], v[232:235], v[90:93]
	v_mfma_f32_16x16x32_bf16 v[82:85], v[184:187], v[232:235], v[82:85]
	v_mfma_f32_16x16x32_bf16 v[74:77], v[176:179], v[240:243], v[74:77]
	v_mfma_f32_16x16x32_bf16 v[66:69], v[184:187], v[240:243], v[66:69]
	v_mfma_f32_16x16x32_bf16 v[122:125], v[180:183], v[220:223], v[122:125]
	v_mfma_f32_16x16x32_bf16 v[114:117], v[212:215], v[220:223], v[114:117]
	v_mfma_f32_16x16x32_bf16 v[106:109], v[180:183], v[228:231], v[106:109]
	v_mfma_f32_16x16x32_bf16 v[98:101], v[212:215], v[228:231], v[98:101]
	v_mfma_f32_16x16x32_bf16 v[90:93], v[180:183], v[236:239], v[90:93]
	v_mfma_f32_16x16x32_bf16 v[82:85], v[212:215], v[236:239], v[82:85]
	v_mfma_f32_16x16x32_bf16 v[74:77], v[180:183], v[244:247], v[74:77]
	v_mfma_f32_16x16x32_bf16 v[66:69], v[212:215], v[244:247], v[66:69]
	s_setprio 0
	s_barrier
	s_add_i32 s40, s55, s7
	v_lshl_add_u64 v[154:155], v[154:155], 0, s[20:21]
	s_mov_b32 m0, s40
	ds_read_b128 v[216:219], v148 offset:49152
	ds_read_b128 v[220:223], v148 offset:50176
	ds_read_b128 v[224:227], v148 offset:51200
	ds_read_b128 v[228:231], v148 offset:52224
	ds_read_b128 v[232:235], v148 offset:53248
	ds_read_b128 v[236:239], v148 offset:54272
	ds_read_b128 v[240:243], v148 offset:55296
	ds_read_b128 v[244:247], v148 offset:56320
	global_load_lds_dwordx4 v[154:155], off
	s_add_i32 m0, s40, 0x2000
	s_add_u32 s38, s38, 0x40080
	v_lshl_add_u64 v[154:155], v[172:173], 0, s[20:21]
	s_addc_u32 s39, s39, 0
	s_add_i32 s40, s56, s7
	global_load_lds_dwordx4 v[154:155], off
	v_lshl_add_u64 v[154:155], s[38:39], 0, v[0:1]
	s_mov_b32 m0, s40
	s_nop 0
	global_load_lds_dwordx4 v[154:155], off
	v_lshl_add_u64 v[154:155], s[38:39], 0, v[134:135]
	s_add_i32 m0, s40, 0x2000
	s_nop 0
	global_load_lds_dwordx4 v[154:155], off
	v_lshl_add_u64 v[154:155], v[248:249], 0, s[20:21]
	s_mov_b32 m0, s46
	s_nop 0
	global_load_lds_dwordx4 v[154:155], off
	v_lshl_add_u64 v[154:155], v[250:251], 0, s[20:21]
	s_mov_b32 m0, s47
	s_nop 0
	global_load_lds_dwordx4 v[154:155], off
	s_waitcnt vmcnt(8)
	s_waitcnt lgkmcnt(0)
	s_barrier
	s_setprio 1
	s_waitcnt lgkmcnt(0)
	v_mfma_f32_16x16x32_bf16 v[62:65], v[140:143], v[216:219], v[62:65]
	v_mfma_f32_16x16x32_bf16 v[54:57], v[164:167], v[216:219], v[54:57]
	v_mfma_f32_16x16x32_bf16 v[46:49], v[140:143], v[224:227], v[46:49]
	v_mfma_f32_16x16x32_bf16 v[38:41], v[164:167], v[224:227], v[38:41]
	v_mfma_f32_16x16x32_bf16 v[30:33], v[140:143], v[232:235], v[30:33]
	v_mfma_f32_16x16x32_bf16 v[22:25], v[164:167], v[232:235], v[22:25]
	v_mfma_f32_16x16x32_bf16 v[14:17], v[140:143], v[240:243], v[14:17]
	v_mfma_f32_16x16x32_bf16 v[6:9], v[164:167], v[240:243], v[6:9]
	v_mfma_f32_16x16x32_bf16 v[62:65], v[150:153], v[220:223], v[62:65]
	v_mfma_f32_16x16x32_bf16 v[54:57], v[168:171], v[220:223], v[54:57]
	v_mfma_f32_16x16x32_bf16 v[46:49], v[150:153], v[228:231], v[46:49]
	v_mfma_f32_16x16x32_bf16 v[38:41], v[168:171], v[228:231], v[38:41]
	v_mfma_f32_16x16x32_bf16 v[30:33], v[150:153], v[236:239], v[30:33]
	v_mfma_f32_16x16x32_bf16 v[22:25], v[168:171], v[236:239], v[22:25]
	v_mfma_f32_16x16x32_bf16 v[14:17], v[150:153], v[244:247], v[14:17]
	v_mfma_f32_16x16x32_bf16 v[6:9], v[168:171], v[244:247], v[6:9]
	s_setprio 0
	s_setprio 1
	v_mfma_f32_16x16x32_bf16 v[58:61], v[176:179], v[216:219], v[58:61]
	v_mfma_f32_16x16x32_bf16 v[50:53], v[184:187], v[216:219], v[50:53]
	v_mfma_f32_16x16x32_bf16 v[42:45], v[176:179], v[224:227], v[42:45]
	v_mfma_f32_16x16x32_bf16 v[34:37], v[184:187], v[224:227], v[34:37]
	s_add_i32 s54, s54, 2
	s_add_u32 s36, s36, 0x100
	s_addc_u32 s37, s37, 0
	s_add_u32 s52, s52, 0x100
	s_addc_u32 s53, s53, 0
	s_cmp_gt_u32 s54, 13
	s_cselect_b32 s59, 1, 0
	s_add_u32 s38, s36, 0xfffc0080
	s_addc_u32 s39, s37, -1
	s_add_i32 s55, 0, 0x10000
	s_cmp_eq_u32 s54, 12
	s_cselect_b32 s41, s17, s39
	s_cselect_b32 s40, s50, s38
	v_add_u32_e32 v149, s55, v145
	s_cselect_b32 s39, s15, s53
	s_cselect_b32 s38, s51, s52
	s_add_i32 s58, 0, 0x14000
	v_mfma_f32_16x16x32_bf16 v[26:29], v[176:179], v[232:235], v[26:29]
	v_mfma_f32_16x16x32_bf16 v[18:21], v[184:187], v[232:235], v[18:21]
	v_mfma_f32_16x16x32_bf16 v[10:13], v[176:179], v[240:243], v[10:13]
	v_mfma_f32_16x16x32_bf16 v[2:5], v[184:187], v[240:243], v[2:5]
	v_mfma_f32_16x16x32_bf16 v[58:61], v[180:183], v[220:223], v[58:61]
	v_mfma_f32_16x16x32_bf16 v[50:53], v[212:215], v[220:223], v[50:53]
	v_mfma_f32_16x16x32_bf16 v[42:45], v[180:183], v[228:231], v[42:45]
	v_mfma_f32_16x16x32_bf16 v[34:37], v[212:215], v[228:231], v[34:37]
	v_mfma_f32_16x16x32_bf16 v[26:29], v[180:183], v[236:239], v[26:29]
	v_mfma_f32_16x16x32_bf16 v[18:21], v[212:215], v[236:239], v[18:21]
	v_mfma_f32_16x16x32_bf16 v[10:13], v[180:183], v[244:247], v[10:13]
	v_mfma_f32_16x16x32_bf16 v[2:5], v[212:215], v[244:247], v[2:5]
	s_setprio 0
	s_barrier
	s_cmp_lg_u32 s59, 0
	s_cbranch_scc0 .LBB0_812
	s_and_b64 vcc, exec, s[12:13]
	s_cbranch_vccz .LBB0_815
	s_barrier
